# dilated loop: K/V rows of chunk ci+2 touched one iteration early (2 dword loads per iteration) so the L2 fill starts earlier
# baseline (speedup 1.0000x reference)
.LBB0_662:
	s_abs_i32 s1, s44
	s_mul_hi_u32 s2, s1, s26
	s_mul_i32 s3, s2, s22
	s_ashr_i32 s0, s44, 31
	s_sub_i32 s1, s1, s3
	s_xor_b32 s0, s0, s25
	s_add_i32 s3, s2, 1
	s_sub_i32 s6, s1, s22
	s_cmp_ge_u32 s1, s22
	s_cselect_b32 s2, s3, s2
	s_cselect_b32 s1, s6, s1
	s_add_i32 s3, s2, 1
	s_cmp_ge_u32 s1, s22
	s_cselect_b32 s1, s3, s2
	s_xor_b32 s1, s1, s0
	s_sub_i32 s2, s1, s0
	s_lshl_b32 s2, s2, 1
	s_add_i32 s2, s2, s44
	s_and_b32 s45, s2, 7
	s_ashr_i32 s2, s44, 7
	s_ashr_i32 s3, s2, 31
	s_min_u32 s46, s45, 4
	s_lshl_b64 s[10:11], s[2:3], 12
	s_add_i32 s65, s46, 1
	s_lshl_b32 s3, s45, 5
	s_lshl_b32 s47, s65, 1
	s_sub_i32 s6, s3, 32
	s_cmp_eq_u32 s45, 0
	v_or_b32_e32 v0, s3, v199
	s_cselect_b32 s2, 4, 8
	s_cselect_b32 s13, 16, 20
	s_cselect_b32 s16, s23, s19
	s_cselect_b32 s17, 0, s6
	s_lshl_b32 s6, s44, 3
	v_lshl_add_u32 v16, v0, 4, s19
	s_and_b32 s48, s6, 0x3c0
	v_lshl_add_u64 v[0:1], s[10:11], 0, v[16:17]
	v_add_u32_e32 v8, 0x80, v16
	v_mov_b32_e32 v9, v17
	v_add_u32_e32 v18, 0x100, v16
	v_mov_b32_e32 v19, v17
	v_add_u32_e32 v16, 0x180, v16
	v_or_b32_e32 v64, s48, v210
	v_lshl_add_u64 v[8:9], s[10:11], 0, v[8:9]
	v_lshl_add_u64 v[18:19], s[10:11], 0, v[18:19]
	v_lshl_add_u64 v[26:27], s[10:11], 0, v[16:17]
	v_lshlrev_b64 v[0:1], 11, v[0:1]
	v_lshlrev_b32_e32 v58, 1, v64
	v_lshlrev_b64 v[8:9], 11, v[8:9]
	v_lshlrev_b64 v[18:19], 11, v[18:19]
	v_lshlrev_b64 v[26:27], 11, v[26:27]
	v_or_b32_e32 v0, v0, v58
	v_or_b32_e32 v8, v8, v58
	v_or_b32_e32 v18, v18, v58
	v_or_b32_e32 v26, v26, v58
	v_lshl_add_u64 v[2:3], s[40:41], 0, v[0:1]
	v_lshl_add_u64 v[4:5], s[42:43], 0, v[0:1]
	v_lshl_add_u64 v[10:11], s[40:41], 0, v[8:9]
	v_lshl_add_u64 v[12:13], s[42:43], 0, v[8:9]
	v_lshl_add_u64 v[20:21], s[40:41], 0, v[18:19]
	v_lshl_add_u64 v[22:23], s[42:43], 0, v[18:19]
	v_lshl_add_u64 v[28:29], s[40:41], 0, v[26:27]
	global_load_dwordx4 v[0:3], v[2:3], off
	s_nop 0
	global_load_dwordx4 v[4:7], v[4:5], off
	s_nop 0
	global_load_dwordx4 v[8:11], v[10:11], off
	s_nop 0
	global_load_dwordx4 v[12:15], v[12:13], off
	s_nop 0
	global_load_dwordx4 v[18:21], v[20:21], off
	s_nop 0
	global_load_dwordx4 v[22:25], v[22:23], off
	v_lshl_add_u64 v[30:31], s[42:43], 0, v[26:27]
	global_load_dwordx4 v[26:29], v[28:29], off
	s_nop 0
	global_load_dwordx4 v[48:51], v[30:31], off
	s_lshl_b32 s12, s45, 9
	s_or_b32 s14, s10, s12
	s_mov_b32 s15, s11
	v_lshl_add_u64 v[30:31], s[14:15], 0, v[202:203]
	s_lshl_b32 s6, s48, 1
	v_lshl_add_u64 v[52:53], v[200:201], 0, s[6:7]
	v_lshlrev_b64 v[206:207], 11, v[30:31]
	v_lshl_add_u64 v[30:31], v[52:53], 0, v[206:207]
	global_load_dwordx4 v[128:131], v[30:31], off
	global_load_dwordx4 v[132:135], v[30:31], off offset:32
	global_load_dwordx4 v[136:139], v[30:31], off offset:64
	global_load_dwordx4 v[140:143], v[30:31], off offset:96
	v_or_b32_e32 v16, s17, v199
	v_lshl_add_u32 v52, v16, 4, s16
	v_ashrrev_i32_e32 v53, 31, v52
	v_lshl_add_u64 v[54:55], s[10:11], 0, v[52:53]
	v_lshlrev_b64 v[54:55], 11, v[54:55]
	v_lshl_add_u64 v[56:57], v[30:31], 0, s[8:9]
	v_add_co_u32_e32 v30, vcc, s27, v30
	v_or_b32_e32 v54, v54, v58
	s_nop 0
	v_addc_co_u32_e32 v31, vcc, 0, v31, vcc
	global_load_dwordx4 v[144:147], v[56:57], off offset:32
	global_load_dwordx4 v[148:151], v[56:57], off offset:64
	global_load_dwordx4 v[152:155], v[30:31], off
	global_load_dwordx4 v[156:159], v[56:57], off offset:96
	s_lshl_b32 s1, s1, 1
	s_add_i32 s1, s29, s1
	s_lshl_b32 s0, s0, 1
	s_sub_i32 s0, s1, s0
	s_and_b32 s0, s0, 7
	v_or_b32_e32 v220, s3, v197
	s_min_u32 s3, s0, 4
	s_or_b32 s51, s12, 0x1e0
	v_add_u32_e32 v221, s12, v202
	v_add_u32_e32 v223, s12, v214
	s_lshl_b32 s1, s0, 9
	s_lshl_b32 s12, s3, 6
	s_add_i32 s6, s47, s2
	s_or_b32 s1, s1, s12
	s_lshl_b32 s2, s2, 5
	s_add_i32 s49, s6, s13
	s_waitcnt vmcnt(15)
	ds_write_b128 v215, v[0:3]
	s_waitcnt vmcnt(14)
	ds_write_b128 v216, v[4:7] offset:4608
	s_waitcnt vmcnt(13)
	ds_write_b128 v215, v[8:11] offset:1152
	s_waitcnt vmcnt(12)
	ds_write_b128 v216, v[12:15] offset:5120
	s_waitcnt vmcnt(11)
	ds_write_b128 v215, v[18:21] offset:2304
	s_waitcnt vmcnt(10)
	ds_write_b128 v216, v[22:25] offset:5632
	s_waitcnt vmcnt(9)
	ds_write_b128 v215, v[26:29] offset:3456
	s_waitcnt vmcnt(8)
	ds_write_b128 v216, v[48:51] offset:6144
	v_lshl_add_u64 v[0:1], s[40:41], 0, v[54:55]
	v_lshl_add_u64 v[2:3], s[42:43], 0, v[54:55]
	global_load_dwordx4 v[160:163], v[0:1], off
	global_load_dwordx4 v[164:167], v[2:3], off
	v_add_u32_e32 v0, 0x80, v52
	v_ashrrev_i32_e32 v1, 31, v0
	v_lshl_add_u64 v[0:1], s[10:11], 0, v[0:1]
	v_lshlrev_b64 v[0:1], 11, v[0:1]
	v_or_b32_e32 v0, v0, v58
	v_lshl_add_u64 v[2:3], s[40:41], 0, v[0:1]
	v_lshl_add_u64 v[0:1], s[42:43], 0, v[0:1]
	global_load_dwordx4 v[168:171], v[2:3], off
	global_load_dwordx4 v[172:175], v[0:1], off
	v_add_u32_e32 v0, 0x100, v52
	v_ashrrev_i32_e32 v1, 31, v0
	v_lshl_add_u64 v[0:1], s[10:11], 0, v[0:1]
	v_lshlrev_b64 v[0:1], 11, v[0:1]
	v_or_b32_e32 v0, v0, v58
	v_lshl_add_u64 v[2:3], s[40:41], 0, v[0:1]
	v_lshl_add_u64 v[0:1], s[42:43], 0, v[0:1]
	global_load_dwordx4 v[176:179], v[2:3], off
	global_load_dwordx4 v[180:183], v[0:1], off
	v_add_u32_e32 v0, 0x180, v52
	v_ashrrev_i32_e32 v1, 31, v0
	v_lshl_add_u64 v[0:1], s[10:11], 0, v[0:1]
	v_lshlrev_b64 v[0:1], 11, v[0:1]
	v_or_b32_e32 v0, v0, v58
	v_lshl_add_u64 v[2:3], s[40:41], 0, v[0:1]
	v_lshl_add_u64 v[0:1], s[42:43], 0, v[0:1]
	global_load_dwordx4 v[184:187], v[2:3], off
	global_load_dwordx4 v[188:191], v[0:1], off
	s_waitcnt lgkmcnt(0)
	ds_read_b128 v[18:21], v217
	ds_read_b128 v[22:25], v217 offset:32
	s_waitcnt vmcnt(15) lgkmcnt(1)
	v_mfma_f32_32x32x16_bf16 v[0:15], v[18:21], v[128:131], v[32:47]
	ds_read_b128 v[18:21], v217 offset:64
	s_lshl_b32 s13, s45, 7
	s_add_i32 s1, s1, s2
	s_lshl_b32 s0, s0, 5
	v_lshlrev_b32_e32 v225, 1, v64
	s_sub_i32 s50, -2, s46
	s_or_b32 s64, s13, 0x60
	s_waitcnt vmcnt(14) lgkmcnt(1)
	v_mfma_f32_32x32x16_bf16 v[0:15], v[22:25], v[132:135], v[0:15]
	s_add_i32 s65, s65, s45
	v_add_u32_e32 v205, s13, v212
	v_add_u32_e32 v222, s13, v213
	s_add_i32 s66, s1, 0x200
	s_sub_i32 s67, s0, 32
	s_lshl_b32 s68, s3, 5
	v_mov_b32_e32 v219, 0
	s_waitcnt vmcnt(13) lgkmcnt(0)
	v_mfma_f32_32x32x16_bf16 v[0:15], v[18:21], v[136:139], v[0:15]
	ds_read_b128 v[18:21], v217 offset:96
	s_mov_b32 s70, 1
	v_mov_b32_e32 v226, 0
	s_waitcnt vmcnt(12) lgkmcnt(0)
	v_mfma_f32_32x32x16_bf16 v[0:15], v[18:21], v[140:143], v[0:15]
	s_nop 11
	v_max_f32_e32 v16, v0, v1
	v_max3_f32 v16, v16, v2, v3
	v_max3_f32 v16, v16, v4, v5
	v_max3_f32 v16, v16, v6, v7
	v_max3_f32 v16, v16, v8, v9
	v_max3_f32 v16, v16, v10, v11
	v_max3_f32 v16, v16, v12, v13
	v_max3_f32 v16, v16, v14, v15
	v_mov_b32_e32 v18, v16
	s_nop 1
	v_permlane32_swap_b32_e32 v16, v18
	v_max_f32_e32 v18, v18, v18
	v_max_f32_e32 v16, v16, v16
	v_max_f32_e32 v23, v16, v18
	v_exp_f32_e64 v16, -v23
	v_sub_f32_e32 v15, v15, v23
	v_sub_f32_e32 v14, v14, v23
	v_sub_f32_e32 v13, v13, v23
	v_sub_f32_e32 v12, v12, v23
	v_sub_f32_e32 v11, v11, v23
	v_sub_f32_e32 v10, v10, v23
	v_sub_f32_e32 v9, v9, v23
	v_sub_f32_e32 v8, v8, v23
	v_sub_f32_e32 v7, v7, v23
	v_sub_f32_e32 v6, v6, v23
	v_sub_f32_e32 v5, v5, v23
	v_sub_f32_e32 v4, v4, v23
	v_sub_f32_e32 v3, v3, v23
	v_sub_f32_e32 v2, v2, v23
	v_sub_f32_e32 v1, v1, v23
	v_sub_f32_e32 v0, v0, v23
	v_exp_f32_e32 v25, v0
	v_exp_f32_e32 v24, v1
	v_exp_f32_e32 v27, v2
	v_exp_f32_e32 v26, v3
	v_exp_f32_e32 v29, v4
	v_exp_f32_e32 v28, v5
	v_exp_f32_e32 v31, v6
	v_exp_f32_e32 v30, v7
	v_exp_f32_e32 v67, v8
	v_exp_f32_e32 v66, v9
	v_exp_f32_e32 v69, v10
	v_exp_f32_e32 v68, v11
	v_exp_f32_e32 v71, v12
	v_exp_f32_e32 v70, v13
	v_exp_f32_e32 v73, v14
	v_exp_f32_e32 v72, v15
	v_cvt_pk_bf16_f32 v0, v25, v24
	v_cvt_pk_bf16_f32 v1, v27, v26
	v_cvt_pk_bf16_f32 v2, v29, v28
	v_cvt_pk_bf16_f32 v3, v31, v30
	v_cvt_pk_bf16_f32 v4, v67, v66
	v_cvt_pk_bf16_f32 v5, v69, v68
	v_cvt_pk_bf16_f32 v6, v71, v70
	v_cvt_pk_bf16_f32 v7, v73, v72
	ds_read_b64_tr_b16 v[8:9], v218 offset:4608
	ds_read_b64_tr_b16 v[10:11], v218 offset:5120
	ds_read_b64_tr_b16 v[12:13], v218 offset:5632
	ds_read_b64_tr_b16 v[14:15], v218 offset:6144
	ds_read_b64_tr_b16 v[18:19], v218 offset:6656
	ds_read_b64_tr_b16 v[20:21], v218 offset:7168
	v_mul_f32_e32 v48, 0, v16
	v_mov_b32_e32 v49, v48
	v_mov_b32_e32 v50, v48
	v_mov_b32_e32 v51, v48
	v_mov_b32_e32 v52, v48
	v_mov_b32_e32 v53, v48
	v_mov_b32_e32 v54, v48
	v_mov_b32_e32 v55, v48
	v_mov_b32_e32 v56, v48
	v_mov_b32_e32 v57, v48
	v_mov_b32_e32 v58, v48
	v_mov_b32_e32 v59, v48
	v_mov_b32_e32 v60, v48
	v_mov_b32_e32 v61, v48
	v_mov_b32_e32 v62, v48
	v_mov_b32_e32 v63, v48
	v_mov_b32_e32 v22, v48
	v_mov_b32_e32 v16, v17
	s_waitcnt lgkmcnt(4)
	v_mfma_f32_32x32x16_bf16 v[96:111], v[8:11], v[0:3], v[48:63]
	ds_read_b64_tr_b16 v[8:9], v218 offset:7680
	ds_read_b64_tr_b16 v[10:11], v218 offset:8192
	s_waitcnt lgkmcnt(0)
	s_waitcnt lgkmcnt(2)
	v_mfma_f32_32x32x16_bf16 v[48:63], v[18:21], v[0:3], v[48:63]
	v_add_f32_e64 v0, v24, 0
	v_add_f32_e64 v1, v25, 0
	v_mov_b32_e32 v18, v17
	v_add_f32_e64 v0, v26, v0
	v_add_f32_e64 v1, v27, v1
	v_mov_b32_e32 v19, v17
	v_pk_add_f32 v[0:1], v[28:29], v[0:1]
	v_mov_b32_e32 v20, v17
	v_pk_add_f32 v[0:1], v[30:31], v[0:1]
	v_mfma_f32_32x32x16_bf16 v[96:111], v[12:15], v[4:7], v[96:111]
	v_add_f32_e64 v0, v66, v0
	v_add_f32_e64 v1, v67, v1
	v_mov_b32_e32 v30, v17
	v_add_f32_e64 v0, v68, v0
	v_add_f32_e64 v1, v69, v1
	v_mov_b32_e32 v31, v17
	v_pk_add_f32 v[0:1], v[70:71], v[0:1]
	v_mov_b32_e32 v21, v17
	v_pk_add_f32 v[0:1], v[72:73], v[0:1]
	s_waitcnt lgkmcnt(0)
	v_mfma_f32_32x32x16_bf16 v[48:63], v[8:11], v[4:7], v[48:63]
	v_pk_add_f32 v[0:1], v[0:1], v[0:1] op_sel:[0,1] op_sel_hi:[1,0]
	v_mov_b32_e32 v24, v17
	v_mov_b32_e32 v1, v17
	v_pk_add_f32 v[208:209], v[22:23], v[0:1]
	v_mov_b32_e32 v22, v17
	v_mov_b32_e32 v23, v17
	v_mov_b32_e32 v25, v17
	v_mov_b32_e32 v26, v17
	v_mov_b32_e32 v27, v17
	v_mov_b32_e32 v28, v17
	v_mov_b32_e32 v29, v17
	v_mov_b64_e32 v[78:79], v[30:31]
	v_mov_b64_e32 v[94:95], v[30:31]
	v_mov_b64_e32 v[76:77], v[28:29]
	v_mov_b64_e32 v[74:75], v[26:27]
	v_mov_b64_e32 v[72:73], v[24:25]
	v_mov_b64_e32 v[70:71], v[22:23]
	v_mov_b64_e32 v[68:69], v[20:21]
	v_mov_b64_e32 v[66:67], v[18:19]
	v_mov_b64_e32 v[64:65], v[16:17]
	v_mov_b64_e32 v[92:93], v[28:29]
	v_mov_b64_e32 v[90:91], v[26:27]
	v_mov_b64_e32 v[88:89], v[24:25]
	v_mov_b64_e32 v[86:87], v[22:23]
	v_mov_b64_e32 v[84:85], v[20:21]
	v_mov_b64_e32 v[82:83], v[18:19]
	v_mov_b64_e32 v[80:81], v[16:17]
	s_mov_b32 s96, 2
	s_add_i32 s97, s49, -1
	s_min_u32 s96, s96, s97
	s_cmp_ge_u32 s96, s47
	s_cbranch_scc0 .Ldd_p16b
	s_cmp_ge_u32 s96, s6
	s_cselect_b32 s0, s6, s47
	s_cselect_b32 s1, s51, s64
	s_cselect_b32 s16, 1, 4
	s_cselect_b32 s17, 0, s24
	s_sub_i32 s0, s0, s96
	s_lshl_b32 s0, s0, 5
	s_add_i32 s0, s0, s1
.Ldd_pdoneb:
	v_add_u32_e32 v243, s0, v197
	v_mul_lo_u32 v243, v243, s16
	v_add_u32_e32 v243, s17, v243
	v_add_u32_e32 v243, s10, v243
	v_lshl_or_b32 v243, v243, 11, v225
	global_load_dword v244, v243, s[40:41]
	global_load_dword v245, v243, s[42:43]
.LBB0_663:
	s_add_i32 s69, s70, 1
	s_cmp_ge_u32 s69, s49
	s_cselect_b64 s[12:13], -1, 0
	s_and_b64 vcc, exec, s[12:13]
	s_waitcnt vmcnt(9)
	ds_write_b128 v215, v[160:163]
	s_waitcnt vmcnt(8)
	ds_write_b128 v216, v[164:167] offset:4608
	s_waitcnt vmcnt(7)
	ds_write_b128 v215, v[168:171] offset:1152
	s_waitcnt vmcnt(6)
	ds_write_b128 v216, v[172:175] offset:5120
	s_waitcnt vmcnt(5)
	ds_write_b128 v215, v[176:179] offset:2304
	s_waitcnt vmcnt(4)
	ds_write_b128 v216, v[180:183] offset:5632
	s_waitcnt vmcnt(3)
	ds_write_b128 v215, v[184:187] offset:3456
	s_waitcnt vmcnt(2)
	ds_write_b128 v216, v[188:191] offset:6144
	s_cbranch_vccnz .LBB0_677
	s_cmp_ge_u32 s69, s47
	s_cbranch_scc0 .Ldd_f16
	s_cmp_ge_u32 s69, s6
	s_cselect_b32 s0, s6, s47
	s_cselect_b32 s1, s51, s64
	s_cselect_b32 s3, 1, 4
	s_cselect_b32 s14, 0, s24
	s_sub_i32 s0, s0, s69
	s_lshl_b32 s0, s0, 5
	s_add_i32 s2, s0, s1
.LBB0_676:
	s_waitcnt lgkmcnt(9)
	v_add_u32_e32 v0, s2, v199
	v_mul_lo_u32 v0, v0, s3
	v_add_u32_e32 v0, s14, v0
	s_waitcnt lgkmcnt(8)
	v_add_u32_e32 v0, s10, v0
	s_lshl_b32 s0, s3, 14
	v_lshl_or_b32 v2, v0, 11, v225
	global_load_dwordx4 v[160:163], v2, s[40:41]
	global_load_dwordx4 v[164:167], v2, s[42:43]
	v_add_u32_e32 v3, s0, v2
	global_load_dwordx4 v[168:171], v3, s[40:41]
	global_load_dwordx4 v[172:175], v3, s[42:43]
	v_add_u32_e32 v4, s0, v3
	global_load_dwordx4 v[176:179], v4, s[40:41]
	global_load_dwordx4 v[180:183], v4, s[42:43]
	v_add_u32_e32 v5, s0, v4
	global_load_dwordx4 v[184:187], v5, s[40:41]
	global_load_dwordx4 v[188:191], v5, s[42:43]
	s_add_i32 s96, s69, 1
	s_add_i32 s97, s49, -1
	s_min_u32 s96, s96, s97
	s_cmp_ge_u32 s96, s47
	s_cbranch_scc0 .Ldd_p16a
	s_cmp_ge_u32 s96, s6
	s_cselect_b32 s0, s6, s47
	s_cselect_b32 s1, s51, s64
	s_cselect_b32 s16, 1, 4
	s_cselect_b32 s17, 0, s24
	s_sub_i32 s0, s0, s96
	s_lshl_b32 s0, s0, 5
	s_add_i32 s0, s0, s1

.Ldd_p16a:
	s_sub_i32 s0, s45, s96
	s_sub_i32 s1, s65, s96
	s_cmp_gt_u32 s96, s46
	s_cselect_b32 s0, s1, s0
	s_cselect_b32 s17, s23, s19
	s_lshl_b32 s0, s0, 5
	s_mov_b32 s16, 16
	s_branch .Ldd_pdonea
